# k5 + grid barrier: non-leader workgroups poll the cross-XCD release word directly, per-XCD release add dropped
# speedup vs baseline: 1.0063x; 1.0063x over previous
.LBB0_465:
	s_or_b64 exec, exec, s[12:13]
	v_cvt_f32_u32_e32 v5, v3
	s_waitcnt vmcnt(0)
	v_readfirstlane_b32 s3, v4
	v_sub_u32_e32 v4, 0, v3
	v_rcp_iflag_f32_e32 v5, v5
	v_add_u32_e32 v6, s3, v2
	v_mul_f32_e32 v5, 0x4f7ffffe, v5
	v_cvt_u32_f32_e32 v5, v5
	v_mul_lo_u32 v2, v4, v5
	v_mul_hi_u32 v2, v5, v2
	v_add_u32_e32 v2, v5, v2
	v_mul_hi_u32 v2, v6, v2
	v_mul_lo_u32 v4, v2, v3
	v_sub_u32_e32 v4, v6, v4
	v_add_u32_e32 v5, 1, v2
	v_cmp_ge_u32_e32 vcc, v4, v3
	s_nop 1
	v_cndmask_b32_e32 v2, v2, v5, vcc
	v_sub_u32_e32 v5, v4, v3
	v_cndmask_b32_e32 v4, v4, v5, vcc
	v_add_u32_e32 v5, 1, v2
	v_cmp_ge_u32_e32 vcc, v4, v3
	v_add_u32_e32 v4, 1, v6
	s_nop 0
	v_cndmask_b32_e32 v2, v2, v5, vcc
	v_mul_lo_u32 v5, v3, v2
	v_add_u32_e32 v3, v5, v3
	v_cmp_ne_u32_e32 vcc, v4, v3
	s_and_saveexec_b64 s[8:9], vcc
	s_xor_b64 s[8:9], exec, s[8:9]
	s_cbranch_execz .LBB0_479
	s_waitcnt lgkmcnt(0)
	v_mov_b32_e32 v1, 0x3000
	global_load_dword v1, v1, s[42:43] offset:1280 sc1
	s_add_u32 s14, s42, 0x3500
	s_addc_u32 s15, s43, 0
	s_waitcnt vmcnt(0)
	v_cmp_eq_u32_e32 vcc, v1, v2
	s_and_saveexec_b64 s[12:13], vcc
	s_cbranch_execz .LBB0_478
	s_mov_b32 s3, 1
	s_mov_b64 s[16:17], 0
	v_mov_b32_e32 v1, 0
	s_branch .LBB0_469

.LBB0_496:
	s_or_b64 exec, exec, s[8:9]
	s_mov_b64 s[8:9], exec
	v_mbcnt_lo_u32_b32 v1, s8, 0
	v_mbcnt_hi_u32_b32 v1, s9, v1
	v_cmp_eq_u32_e32 vcc, 0, v1
	s_waitcnt vmcnt(0)
	buffer_inv sc1
	s_and_saveexec_b64 s[12:13], vcc
	s_cbranch_execz .LBB0_498
	s_bcnt1_i32_b64 s3, s[8:9]
	v_mov_b32_e32 v1, 0x2000
	v_mov_b32_e32 v2, s3
.LBB0_498:
	s_or_b64 exec, exec, s[12:13]
	s_waitcnt vmcnt(0)

.LBB0_589:
	s_or_b64 exec, exec, s[8:9]
	s_mov_b64 s[8:9], exec
	v_mbcnt_lo_u32_b32 v1, s8, 0
	v_mbcnt_hi_u32_b32 v1, s9, v1
	v_cmp_eq_u32_e32 vcc, 0, v1
	s_waitcnt vmcnt(0)
	buffer_inv sc1
	s_and_saveexec_b64 s[12:13], vcc
	s_cbranch_execz .LBB0_591
	s_bcnt1_i32_b64 s3, s[8:9]
	v_mov_b32_e32 v1, 0x2000
	v_mov_b32_e32 v2, s3
.LBB0_591:
	s_or_b64 exec, exec, s[12:13]
	s_waitcnt vmcnt(0)

.LBB0_653:
	s_or_b64 exec, exec, s[8:9]
	s_mov_b64 s[8:9], exec
	v_mbcnt_lo_u32_b32 v1, s8, 0
	v_mbcnt_hi_u32_b32 v1, s9, v1
	v_cmp_eq_u32_e32 vcc, 0, v1
	s_waitcnt vmcnt(0)
	buffer_inv sc1
	s_and_saveexec_b64 s[12:13], vcc
	s_cbranch_execz .LBB0_655
	s_bcnt1_i32_b64 s3, s[8:9]
	v_mov_b32_e32 v1, 0x2000
	v_mov_b32_e32 v2, s3
.LBB0_655:
	s_or_b64 exec, exec, s[12:13]
	s_waitcnt vmcnt(0)

.LBB0_1174:
	s_or_b64 exec, exec, s[8:9]
	s_mov_b64 s[8:9], exec
	v_mbcnt_lo_u32_b32 v1, s8, 0
	v_mbcnt_hi_u32_b32 v1, s9, v1
	v_cmp_eq_u32_e32 vcc, 0, v1
	s_waitcnt vmcnt(0)
	buffer_inv sc1
	s_and_saveexec_b64 s[12:13], vcc
	s_cbranch_execz .LBB0_1176
	s_bcnt1_i32_b64 s3, s[8:9]
	v_mov_b32_e32 v1, 0x2000
	v_mov_b32_e32 v2, s3
.LBB0_1176:
	s_or_b64 exec, exec, s[12:13]
	s_waitcnt vmcnt(0)

.LBB0_1693:
	s_or_b64 exec, exec, s[8:9]
	s_mov_b64 s[8:9], exec
	v_mbcnt_lo_u32_b32 v1, s8, 0
	v_mbcnt_hi_u32_b32 v1, s9, v1
	v_cmp_eq_u32_e32 vcc, 0, v1
	s_waitcnt vmcnt(0)
	buffer_inv sc1
	s_and_saveexec_b64 s[12:13], vcc
	s_cbranch_execz .LBB0_1695
	s_bcnt1_i32_b64 s3, s[8:9]
	v_mov_b32_e32 v1, 0x2000
	v_mov_b32_e32 v2, s3
.LBB0_1695:
	s_or_b64 exec, exec, s[12:13]
	s_waitcnt vmcnt(0)

.LBB0_1861:
	s_or_b64 exec, exec, s[8:9]
	s_mov_b64 s[8:9], exec
	v_mbcnt_lo_u32_b32 v1, s8, 0
	v_mbcnt_hi_u32_b32 v1, s9, v1
	v_cmp_eq_u32_e32 vcc, 0, v1
	s_waitcnt vmcnt(0)
	buffer_inv sc1
	s_and_saveexec_b64 s[12:13], vcc
	s_cbranch_execz .LBB0_1863
	s_bcnt1_i32_b64 s3, s[8:9]
	v_mov_b32_e32 v1, 0x2000
	v_mov_b32_e32 v2, s3
.LBB0_1863:
	s_or_b64 exec, exec, s[12:13]
	s_waitcnt vmcnt(0)

.LBB0_1989:
	s_or_b64 exec, exec, s[8:9]
	s_mov_b64 s[8:9], exec
	v_mbcnt_lo_u32_b32 v1, s8, 0
	v_mbcnt_hi_u32_b32 v1, s9, v1
	v_cmp_eq_u32_e32 vcc, 0, v1
	s_waitcnt vmcnt(0)
	buffer_inv sc1
	s_and_saveexec_b64 s[12:13], vcc
	s_cbranch_execz .LBB0_1991
	s_bcnt1_i32_b64 s3, s[8:9]
	v_mov_b32_e32 v1, 0x2000
	v_mov_b32_e32 v2, s3
.LBB0_1991:
	s_or_b64 exec, exec, s[12:13]
	s_waitcnt vmcnt(0)

.LBB0_2082:
	s_or_b64 exec, exec, s[8:9]
	s_mov_b64 s[8:9], exec
	v_mbcnt_lo_u32_b32 v1, s8, 0
	v_mbcnt_hi_u32_b32 v1, s9, v1
	v_cmp_eq_u32_e32 vcc, 0, v1
	s_waitcnt vmcnt(0)
	buffer_inv sc1
	s_and_saveexec_b64 s[12:13], vcc
	s_cbranch_execz .LBB0_2084
	s_bcnt1_i32_b64 s3, s[8:9]
	v_mov_b32_e32 v1, 0x2000
	v_mov_b32_e32 v2, s3
.LBB0_2084:
	s_or_b64 exec, exec, s[12:13]
	s_waitcnt vmcnt(0)

.LBB0_2939:
	s_or_b64 exec, exec, s[8:9]
	s_mov_b64 s[8:9], exec
	v_mbcnt_lo_u32_b32 v1, s8, 0
	v_mbcnt_hi_u32_b32 v1, s9, v1
	v_cmp_eq_u32_e32 vcc, 0, v1
	s_waitcnt vmcnt(0)
	buffer_inv sc1
	s_and_saveexec_b64 s[12:13], vcc
	s_cbranch_execz .LBB0_2941
	s_bcnt1_i32_b64 s3, s[8:9]
	v_mov_b32_e32 v1, 0x2000
	v_mov_b32_e32 v2, s3
.LBB0_2941:
	s_or_b64 exec, exec, s[12:13]
	s_waitcnt vmcnt(0)

.LBB0_3019:
	s_or_b64 exec, exec, s[8:9]
	s_mov_b64 s[8:9], exec
	v_mbcnt_lo_u32_b32 v1, s8, 0
	v_mbcnt_hi_u32_b32 v1, s9, v1
	v_cmp_eq_u32_e32 vcc, 0, v1
	s_waitcnt vmcnt(0)
	buffer_inv sc1
	s_and_saveexec_b64 s[12:13], vcc
	s_cbranch_execz .LBB0_3021
	s_bcnt1_i32_b64 s3, s[8:9]
	v_mov_b32_e32 v1, 0x2000
	v_mov_b32_e32 v2, s3
.LBB0_3021:
	s_or_b64 exec, exec, s[12:13]
	s_waitcnt vmcnt(0)

.LBB0_3237:
	s_or_b64 exec, exec, s[8:9]
	s_mov_b64 s[8:9], exec
	v_mbcnt_lo_u32_b32 v1, s8, 0
	v_mbcnt_hi_u32_b32 v1, s9, v1
	v_cmp_eq_u32_e32 vcc, 0, v1
	s_waitcnt vmcnt(0)
	buffer_inv sc1
	s_and_saveexec_b64 s[12:13], vcc
	s_cbranch_execz .LBB0_3239
	s_bcnt1_i32_b64 s3, s[8:9]
	v_mov_b32_e32 v1, 0x2000
	v_mov_b32_e32 v2, s3
.LBB0_3239:
	s_or_b64 exec, exec, s[12:13]
	s_waitcnt vmcnt(0)

.LBB0_3736:
	s_or_b64 exec, exec, s[8:9]
	s_mov_b64 s[8:9], exec
	v_mbcnt_lo_u32_b32 v1, s8, 0
	v_mbcnt_hi_u32_b32 v1, s9, v1
	v_cmp_eq_u32_e32 vcc, 0, v1
	s_waitcnt vmcnt(0)
	buffer_inv sc1
	s_and_saveexec_b64 s[12:13], vcc
	s_cbranch_execz .LBB0_3738
	s_bcnt1_i32_b64 s3, s[8:9]
	v_mov_b32_e32 v1, 0x2000
	v_mov_b32_e32 v2, s3
.LBB0_3738:
	s_or_b64 exec, exec, s[12:13]
	s_waitcnt vmcnt(0)

.LBB0_3898:
	s_or_b64 exec, exec, s[8:9]
	s_mov_b64 s[8:9], exec
	v_mbcnt_lo_u32_b32 v1, s8, 0
	v_mbcnt_hi_u32_b32 v1, s9, v1
	v_cmp_eq_u32_e32 vcc, 0, v1
	s_waitcnt vmcnt(0)
	buffer_inv sc1
	s_and_saveexec_b64 s[12:13], vcc
	s_cbranch_execz .LBB0_3900
	s_bcnt1_i32_b64 s3, s[8:9]
	v_mov_b32_e32 v1, 0x2000
	v_mov_b32_e32 v2, s3
.LBB0_3900:
	s_or_b64 exec, exec, s[12:13]
	s_waitcnt vmcnt(0)

.LBB0_4026:
	s_or_b64 exec, exec, s[8:9]
	s_mov_b64 s[8:9], exec
	v_mbcnt_lo_u32_b32 v1, s8, 0
	v_mbcnt_hi_u32_b32 v1, s9, v1
	v_cmp_eq_u32_e32 vcc, 0, v1
	s_waitcnt vmcnt(0)
	buffer_inv sc1
	s_and_saveexec_b64 s[12:13], vcc
	s_cbranch_execz .LBB0_4028
	s_bcnt1_i32_b64 s3, s[8:9]
	v_mov_b32_e32 v1, 0x2000
	v_mov_b32_e32 v2, s3
.LBB0_4028:
	s_or_b64 exec, exec, s[12:13]
	s_waitcnt vmcnt(0)

.LBB0_4117:
	s_or_b64 exec, exec, s[8:9]
	s_mov_b64 s[8:9], exec
	v_mbcnt_lo_u32_b32 v1, s8, 0
	v_mbcnt_hi_u32_b32 v1, s9, v1
	v_cmp_eq_u32_e32 vcc, 0, v1
	s_waitcnt vmcnt(0)
	buffer_inv sc1
	s_and_saveexec_b64 s[12:13], vcc
	s_cbranch_execz .LBB0_4119
	s_bcnt1_i32_b64 s3, s[8:9]
	v_mov_b32_e32 v1, 0x2000
	v_mov_b32_e32 v2, s3
.LBB0_4119:
	s_or_b64 exec, exec, s[12:13]
	s_waitcnt vmcnt(0)

.LBB0_4158:
	s_or_b64 exec, exec, s[10:11]
	v_cvt_f32_u32_e32 v5, v3
	s_waitcnt vmcnt(0)
	v_readfirstlane_b32 s3, v4
	v_sub_u32_e32 v4, 0, v3
	v_rcp_iflag_f32_e32 v5, v5
	v_add_u32_e32 v6, s3, v2
	v_mul_f32_e32 v5, 0x4f7ffffe, v5
	v_cvt_u32_f32_e32 v5, v5
	v_mul_lo_u32 v2, v4, v5
	v_mul_hi_u32 v2, v5, v2
	v_add_u32_e32 v2, v5, v2
	v_mul_hi_u32 v2, v6, v2
	v_mul_lo_u32 v4, v2, v3
	v_sub_u32_e32 v4, v6, v4
	v_add_u32_e32 v5, 1, v2
	v_cmp_ge_u32_e32 vcc, v4, v3
	s_nop 1
	v_cndmask_b32_e32 v2, v2, v5, vcc
	v_sub_u32_e32 v5, v4, v3
	v_cndmask_b32_e32 v4, v4, v5, vcc
	v_add_u32_e32 v5, 1, v2
	v_cmp_ge_u32_e32 vcc, v4, v3
	v_add_u32_e32 v4, 1, v6
	s_nop 0
	v_cndmask_b32_e32 v2, v2, v5, vcc
	v_mul_lo_u32 v5, v3, v2
	v_add_u32_e32 v3, v5, v3
	v_cmp_ne_u32_e32 vcc, v4, v3
	s_and_saveexec_b64 s[8:9], vcc
	s_xor_b64 s[8:9], exec, s[8:9]
	s_cbranch_execz .LBB0_4172
	s_waitcnt lgkmcnt(0)
	v_mov_b32_e32 v1, 0x3000
	global_load_dword v1, v1, s[42:43] offset:1280 sc1
	s_add_u32 s12, s42, 0x3500
	s_addc_u32 s13, s43, 0
	s_waitcnt vmcnt(0)
	v_cmp_eq_u32_e32 vcc, v1, v2
	s_and_saveexec_b64 s[10:11], vcc
	s_cbranch_execz .LBB0_4171
	s_mov_b32 s3, 1
	s_mov_b64 s[14:15], 0
	v_mov_b32_e32 v1, 0
	s_branch .LBB0_4162

.LBB0_4189:
	s_or_b64 exec, exec, s[8:9]
	s_mov_b64 s[8:9], exec
	v_mbcnt_lo_u32_b32 v1, s8, 0
	v_mbcnt_hi_u32_b32 v1, s9, v1
	v_cmp_eq_u32_e32 vcc, 0, v1
	s_waitcnt vmcnt(0)
	buffer_inv sc1
	s_and_saveexec_b64 s[10:11], vcc
	s_cbranch_execz .LBB0_4191
	s_bcnt1_i32_b64 s3, s[8:9]
	v_mov_b32_e32 v1, 0x2000
	v_mov_b32_e32 v2, s3
.LBB0_4191:
	s_or_b64 exec, exec, s[10:11]
	s_waitcnt vmcnt(0)
